# s_setprio 3 also for the lru_prompt chain items of MIX-2
# speedup vs baseline: 1.0039x; 1.0039x over previous
.LBB0_707:
	s_andn2_b64 vcc, exec, s[2:3]
	s_cbranch_vccnz .LBB0_757
	s_setprio 3
	v_mov_b32_e32 v0, v216
	s_sub_i32 s2, s21, 32
	v_readfirstlane_b32 s10, v0
	s_ashr_i32 s8, s10, 6
	s_lshr_b32 s12, s2, 2
	s_lshl_b32 s2, s21, 6
	s_lshl_b32 s9, s8, 9
	s_and_b32 s2, s2, 0xc0
	s_add_i32 s11, s9, 0x200
	v_and_b32_e32 v7, 63, v0
	s_cmp_eq_u32 s8, 3
	v_or_b32_e32 v6, s2, v7
	s_cselect_b64 s[2:3], -1, 0
	s_and_b64 s[4:5], s[2:3], exec
	s_cselect_b32 s14, 0x810, s11
	v_mov_b32_e32 v3, 0
	s_cmp_lt_i32 s9, s14
	s_mul_i32 s13, s12, 0x810
	s_cselect_b64 s[4:5], -1, 0
	s_cmp_ge_i32 s9, s14
	v_lshlrev_b32_e32 v200, 1, v6
	v_mov_b32_e32 v2, v3
	s_cbranch_scc1 .LBB0_711
	s_add_i32 s16, s13, s9
	s_ashr_i32 s17, s16, 31
	s_lshl_b64 s[16:17], s[16:17], 9
	v_readlane_b32 s11, v254, 58
	s_add_u32 s16, s11, s16
	v_readlane_b32 s11, v254, 59
	s_addc_u32 s17, s11, s17
	v_mov_b32_e32 v3, 0
	v_lshl_add_u64 v[0:1], s[16:17], 0, v[200:201]
	v_mov_b32_e32 v2, v3
	s_mov_b32 s11, s9
	s_mov_b64 s[16:17], 0x1000
